# grid barrier rewritten: last-in-XCD (return atomic, hardcoded 32) flushes L2 then bumps 8 per-XCD go words; all WGs poll own go word; no TOP/TOPGEN/XGEN hops
# speedup vs baseline: 1.0063x; 1.0063x over previous
; __device__ __forceinline__ unsigned xb_ld(unsigned* p)              { return __hip_atomic_load(p, __ATOMIC_RELAXED, __HIP_MEMORY_SCOPE_AGENT); }
; __device__ __forceinline__ unsigned xb_add(unsigned* p, unsigned v) { return __hip_atomic_fetch_add(p, v, __ATOMIC_RELAXED, __HIP_MEMORY_SCOPE_AGENT); }
; #define XB_SPIN(cond, bar) do { unsigned _sp = 0; while (cond) { __builtin_amdgcn_s_sleep(1); \
;     if ((++_sp & 255u) == 0u) { if (xb_ld(&(bar)[XB_TMO])) break; if (_sp > XB_SPIN_CAP) { atomicAdd(&(bar)[XB_TMO], 1u); break; } } } } while (0)
; __device__ __forceinline__ void xcd_barrier(const XcdBarrier& b) {
;     asm volatile("s_waitcnt vmcnt(0)" ::: "memory");
;     __syncthreads();
;     if (threadIdx.x == 0) {
;         unsigned* bar = b.bar;
;         __builtin_amdgcn_s_waitcnt(0);
;         unsigned nloc = b.st[0], nx = b.st[1];
;         if (nloc == 0u) { xcd_barrier_complete(bar, b.x, nloc, nx); b.st[0] = nloc; b.st[1] = nx; }
;         const unsigned old = xb_add(&bar[XB_XSUB(b.x)], 1u);
;         const unsigned gen = old / nloc;
;         if (old + 1u == (gen + 1u) * nloc) {
;             __builtin_amdgcn_fence(__ATOMIC_RELEASE, "agent");
;             asm volatile("s_waitcnt vmcnt(0)" ::: "memory");
;             const unsigned og = xb_add(&bar[XB_TOP], 1u);
;             const unsigned tg = og / nx;
;             if (og + 1u == (tg + 1u) * nx) xb_add(&bar[XB_TOPGEN], 1u);
;             else XB_SPIN(xb_ld(&bar[XB_TOPGEN]) == tg, bar);
;             __builtin_amdgcn_fence(__ATOMIC_ACQUIRE, "agent");
;             xb_add(&bar[XB_XGEN(b.x)], 1u);
;             asm volatile("s_waitcnt vmcnt(0)" ::: "memory");
;         } else {
;             XB_SPIN(xb_ld(&bar[XB_XGEN(b.x)]) == gen, bar);
;             __builtin_amdgcn_fence(__ATOMIC_ACQUIRE, "agent");
;             asm volatile("s_waitcnt vmcnt(0)" ::: "memory");
;         }
;     }
;     __syncthreads();
; }
.LBB0_120:
	s_waitcnt vmcnt(0)
	s_barrier
	s_and_saveexec_b64 s[4:5], s[84:85]
	s_cbranch_execz .LBB0_172
	s_and_b32 s3, s91, 7
	s_lshl_b32 s3, s3, 7
	s_add_u32 s8, s96, 0x4000
	s_addc_u32 s9, s97, 0
	s_add_u32 s6, s8, s3
	s_addc_u32 s7, s9, 0
	v_mov_b32_e32 v1, 0
	v_mov_b32_e32 v2, 1
	s_mov_b32 s12, 0
	s_waitcnt vmcnt(0) lgkmcnt(0)
	global_atomic_add v3, v1, v2, s[6:7] sc0
	s_waitcnt vmcnt(0)
	v_cmp_eq_u32_e32 vcc, 31, v3
	s_cbranch_vccz .Lgb0_poll
	buffer_wbl2 sc1
	s_waitcnt vmcnt(0)
	global_atomic_add v1, v2, s[8:9] offset:1024
	global_atomic_add v1, v2, s[8:9] offset:1152
	global_atomic_add v1, v2, s[8:9] offset:1280
	global_atomic_add v1, v2, s[8:9] offset:1408
	global_atomic_add v1, v2, s[8:9] offset:1536
	global_atomic_add v1, v2, s[8:9] offset:1664
	global_atomic_add v1, v2, s[8:9] offset:1792
	global_atomic_add v1, v2, s[8:9] offset:1920
.Lgb0_poll:
	global_load_dword v4, v1, s[6:7] offset:1024 sc1
	s_waitcnt vmcnt(0)
	v_cmp_eq_u32_e32 vcc, 8, v4
	s_cbranch_vccnz .Lgb0_done
	s_sleep 1
	s_add_i32 s12, s12, 1
	s_cmp_lt_u32 s12, 0x10000
	s_cbranch_scc1 .Lgb0_poll
.Lgb0_done:
	buffer_inv sc1
	s_waitcnt vmcnt(0)

; __device__ __forceinline__ unsigned xb_ld(unsigned* p)              { return __hip_atomic_load(p, __ATOMIC_RELAXED, __HIP_MEMORY_SCOPE_AGENT); }
; __device__ __forceinline__ unsigned xb_add(unsigned* p, unsigned v) { return __hip_atomic_fetch_add(p, v, __ATOMIC_RELAXED, __HIP_MEMORY_SCOPE_AGENT); }
; #define XB_SPIN(cond, bar) do { unsigned _sp = 0; while (cond) { __builtin_amdgcn_s_sleep(1); \
;     if ((++_sp & 255u) == 0u) { if (xb_ld(&(bar)[XB_TMO])) break; if (_sp > XB_SPIN_CAP) { atomicAdd(&(bar)[XB_TMO], 1u); break; } } } } while (0)
; __device__ __forceinline__ void xcd_barrier(const XcdBarrier& b) {
;     asm volatile("s_waitcnt vmcnt(0)" ::: "memory");
;     __syncthreads();
;     if (threadIdx.x == 0) {
;         unsigned* bar = b.bar;
;         __builtin_amdgcn_s_waitcnt(0);
;         unsigned nloc = b.st[0], nx = b.st[1];
;         if (nloc == 0u) { xcd_barrier_complete(bar, b.x, nloc, nx); b.st[0] = nloc; b.st[1] = nx; }
;         const unsigned old = xb_add(&bar[XB_XSUB(b.x)], 1u);
;         const unsigned gen = old / nloc;
;         if (old + 1u == (gen + 1u) * nloc) {
;             __builtin_amdgcn_fence(__ATOMIC_RELEASE, "agent");
;             asm volatile("s_waitcnt vmcnt(0)" ::: "memory");
;             const unsigned og = xb_add(&bar[XB_TOP], 1u);
;             const unsigned tg = og / nx;
;             if (og + 1u == (tg + 1u) * nx) xb_add(&bar[XB_TOPGEN], 1u);
;             else XB_SPIN(xb_ld(&bar[XB_TOPGEN]) == tg, bar);
.LBB0_191:
	s_cmp_gt_i32 s95, 2
	s_cbranch_scc0 .LBB0_245
	s_waitcnt vmcnt(0)
	s_barrier
	s_and_saveexec_b64 s[4:5], s[84:85]
	s_cbranch_execz .LBB0_244
	s_and_b32 s3, s91, 7
	s_lshl_b32 s3, s3, 7
	s_add_u32 s8, s96, 0x4800
	s_addc_u32 s9, s97, 0
	s_add_u32 s6, s8, s3
	s_addc_u32 s7, s9, 0
	v_mov_b32_e32 v1, 0
	v_mov_b32_e32 v2, 1
	s_mov_b32 s10, 0
	s_waitcnt vmcnt(0) lgkmcnt(0)
	global_atomic_add v3, v1, v2, s[6:7] sc0
	s_waitcnt vmcnt(0)
	v_cmp_eq_u32_e32 vcc, 31, v3
	s_cbranch_vccz .Lgb1_poll
	buffer_wbl2 sc1
	s_waitcnt vmcnt(0)
	global_atomic_add v1, v2, s[8:9] offset:1024
	global_atomic_add v1, v2, s[8:9] offset:1152
	global_atomic_add v1, v2, s[8:9] offset:1280
	global_atomic_add v1, v2, s[8:9] offset:1408
	global_atomic_add v1, v2, s[8:9] offset:1536
	global_atomic_add v1, v2, s[8:9] offset:1664
	global_atomic_add v1, v2, s[8:9] offset:1792
	global_atomic_add v1, v2, s[8:9] offset:1920
.Lgb1_poll:
	global_load_dword v4, v1, s[6:7] offset:1024 sc1
	s_waitcnt vmcnt(0)
	v_cmp_eq_u32_e32 vcc, 8, v4
	s_cbranch_vccnz .Lgb1_done
	s_sleep 1
	s_add_i32 s10, s10, 1
	s_cmp_lt_u32 s10, 0x10000
	s_cbranch_scc1 .Lgb1_poll

; __device__ __forceinline__ unsigned xb_ld(unsigned* p)              { return __hip_atomic_load(p, __ATOMIC_RELAXED, __HIP_MEMORY_SCOPE_AGENT); }
; __device__ __forceinline__ unsigned xb_add(unsigned* p, unsigned v) { return __hip_atomic_fetch_add(p, v, __ATOMIC_RELAXED, __HIP_MEMORY_SCOPE_AGENT); }
; #define XB_SPIN(cond, bar) do { unsigned _sp = 0; while (cond) { __builtin_amdgcn_s_sleep(1); \
;     if ((++_sp & 255u) == 0u) { if (xb_ld(&(bar)[XB_TMO])) break; if (_sp > XB_SPIN_CAP) { atomicAdd(&(bar)[XB_TMO], 1u); break; } } } } while (0)
; __device__ __forceinline__ void xcd_barrier(const XcdBarrier& b) {
;     asm volatile("s_waitcnt vmcnt(0)" ::: "memory");
;     __syncthreads();
;     if (threadIdx.x == 0) {
;         unsigned* bar = b.bar;
;         __builtin_amdgcn_s_waitcnt(0);
;         unsigned nloc = b.st[0], nx = b.st[1];
;         if (nloc == 0u) { xcd_barrier_complete(bar, b.x, nloc, nx); b.st[0] = nloc; b.st[1] = nx; }
;         const unsigned old = xb_add(&bar[XB_XSUB(b.x)], 1u);
;         const unsigned gen = old / nloc;
;         if (old + 1u == (gen + 1u) * nloc) {
;             __builtin_amdgcn_fence(__ATOMIC_RELEASE, "agent");
;             asm volatile("s_waitcnt vmcnt(0)" ::: "memory");
;             const unsigned og = xb_add(&bar[XB_TOP], 1u);
;             const unsigned tg = og / nx;
;             if (og + 1u == (tg + 1u) * nx) xb_add(&bar[XB_TOPGEN], 1u);
;             else XB_SPIN(xb_ld(&bar[XB_TOPGEN]) == tg, bar);
.LBB0_479:
	s_cmp_lt_i32 s95, 4
	s_cbranch_scc1 .LBB0_533
	s_waitcnt vmcnt(0)
	s_barrier
	s_and_saveexec_b64 s[4:5], s[84:85]
	s_cbranch_execz .LBB0_532
	s_and_b32 s10, s91, 7
	s_lshl_b32 s10, s10, 7
	s_add_u32 s8, s96, 0x5000
	s_addc_u32 s9, s97, 0
	s_add_u32 s6, s8, s10
	s_addc_u32 s7, s9, 0
	v_mov_b32_e32 v1, 0
	v_mov_b32_e32 v2, 1
	s_mov_b32 s11, 0
	s_waitcnt vmcnt(0) lgkmcnt(0)
	global_atomic_add v3, v1, v2, s[6:7] sc0
	s_waitcnt vmcnt(0)
	v_cmp_eq_u32_e32 vcc, 31, v3
	s_cbranch_vccz .Lgb2_poll
	buffer_wbl2 sc1
	s_waitcnt vmcnt(0)
	global_atomic_add v1, v2, s[8:9] offset:1024
	global_atomic_add v1, v2, s[8:9] offset:1152
	global_atomic_add v1, v2, s[8:9] offset:1280
	global_atomic_add v1, v2, s[8:9] offset:1408
	global_atomic_add v1, v2, s[8:9] offset:1536
	global_atomic_add v1, v2, s[8:9] offset:1664
	global_atomic_add v1, v2, s[8:9] offset:1792
	global_atomic_add v1, v2, s[8:9] offset:1920
.Lgb2_poll:
	global_load_dword v4, v1, s[6:7] offset:1024 sc1
	s_waitcnt vmcnt(0)
	v_cmp_eq_u32_e32 vcc, 8, v4
	s_cbranch_vccnz .Lgb2_done
	s_sleep 1
	s_add_i32 s11, s11, 1
	s_cmp_lt_u32 s11, 0x10000
	s_cbranch_scc1 .Lgb2_poll

; __device__ __forceinline__ unsigned xb_ld(unsigned* p)              { return __hip_atomic_load(p, __ATOMIC_RELAXED, __HIP_MEMORY_SCOPE_AGENT); }
; __device__ __forceinline__ unsigned xb_add(unsigned* p, unsigned v) { return __hip_atomic_fetch_add(p, v, __ATOMIC_RELAXED, __HIP_MEMORY_SCOPE_AGENT); }
; #define XB_SPIN(cond, bar) do { unsigned _sp = 0; while (cond) { __builtin_amdgcn_s_sleep(1); \
;     if ((++_sp & 255u) == 0u) { if (xb_ld(&(bar)[XB_TMO])) break; if (_sp > XB_SPIN_CAP) { atomicAdd(&(bar)[XB_TMO], 1u); break; } } } } while (0)
; __device__ __forceinline__ void xcd_barrier(const XcdBarrier& b) {
;     asm volatile("s_waitcnt vmcnt(0)" ::: "memory");
;     __syncthreads();
;     if (threadIdx.x == 0) {
;         unsigned* bar = b.bar;
;         __builtin_amdgcn_s_waitcnt(0);
;         unsigned nloc = b.st[0], nx = b.st[1];
;         if (nloc == 0u) { xcd_barrier_complete(bar, b.x, nloc, nx); b.st[0] = nloc; b.st[1] = nx; }
;         const unsigned old = xb_add(&bar[XB_XSUB(b.x)], 1u);
;         const unsigned gen = old / nloc;
;         if (old + 1u == (gen + 1u) * nloc) {
;             __builtin_amdgcn_fence(__ATOMIC_RELEASE, "agent");
;             asm volatile("s_waitcnt vmcnt(0)" ::: "memory");
;             const unsigned og = xb_add(&bar[XB_TOP], 1u);
;             const unsigned tg = og / nx;
;             if (og + 1u == (tg + 1u) * nx) xb_add(&bar[XB_TOPGEN], 1u);
;             else XB_SPIN(xb_ld(&bar[XB_TOPGEN]) == tg, bar);
.LBB0_563:
	s_cmp_gt_i32 s95, 4
	s_cbranch_scc0 .LBB0_617
	s_waitcnt vmcnt(0)
	s_barrier
	s_and_saveexec_b64 s[4:5], s[84:85]
	s_cbranch_execz .LBB0_616
	s_and_b32 s12, s91, 7
	s_lshl_b32 s12, s12, 7
	s_add_u32 s10, s96, 0x5800
	s_addc_u32 s11, s97, 0
	s_add_u32 s8, s10, s12
	s_addc_u32 s9, s11, 0
	v_mov_b32_e32 v1, 0
	v_mov_b32_e32 v2, 1
	s_mov_b32 s13, 0
	s_waitcnt vmcnt(0) lgkmcnt(0)
	global_atomic_add v3, v1, v2, s[8:9] sc0
	s_waitcnt vmcnt(0)
	v_cmp_eq_u32_e32 vcc, 31, v3
	s_cbranch_vccz .Lgb3_poll
	buffer_wbl2 sc1
	s_waitcnt vmcnt(0)
	global_atomic_add v1, v2, s[10:11] offset:1024
	global_atomic_add v1, v2, s[10:11] offset:1152
	global_atomic_add v1, v2, s[10:11] offset:1280
	global_atomic_add v1, v2, s[10:11] offset:1408
	global_atomic_add v1, v2, s[10:11] offset:1536
	global_atomic_add v1, v2, s[10:11] offset:1664
	global_atomic_add v1, v2, s[10:11] offset:1792
	global_atomic_add v1, v2, s[10:11] offset:1920
.Lgb3_poll:
	global_load_dword v4, v1, s[8:9] offset:1024 sc1
	s_waitcnt vmcnt(0)
	v_cmp_eq_u32_e32 vcc, 8, v4
	s_cbranch_vccnz .Lgb3_done
	s_sleep 1
	s_add_i32 s13, s13, 1
	s_cmp_lt_u32 s13, 0x10000
	s_cbranch_scc1 .Lgb3_poll

; __device__ __forceinline__ unsigned xb_ld(unsigned* p)              { return __hip_atomic_load(p, __ATOMIC_RELAXED, __HIP_MEMORY_SCOPE_AGENT); }
; __device__ __forceinline__ unsigned xb_add(unsigned* p, unsigned v) { return __hip_atomic_fetch_add(p, v, __ATOMIC_RELAXED, __HIP_MEMORY_SCOPE_AGENT); }
; #define XB_SPIN(cond, bar) do { unsigned _sp = 0; while (cond) { __builtin_amdgcn_s_sleep(1); \
;     if ((++_sp & 255u) == 0u) { if (xb_ld(&(bar)[XB_TMO])) break; if (_sp > XB_SPIN_CAP) { atomicAdd(&(bar)[XB_TMO], 1u); break; } } } } while (0)
; __device__ __forceinline__ void xcd_barrier(const XcdBarrier& b) {
;     asm volatile("s_waitcnt vmcnt(0)" ::: "memory");
;     __syncthreads();
;     if (threadIdx.x == 0) {
;         unsigned* bar = b.bar;
;         __builtin_amdgcn_s_waitcnt(0);
;         unsigned nloc = b.st[0], nx = b.st[1];
;         if (nloc == 0u) { xcd_barrier_complete(bar, b.x, nloc, nx); b.st[0] = nloc; b.st[1] = nx; }
;         const unsigned old = xb_add(&bar[XB_XSUB(b.x)], 1u);
;         const unsigned gen = old / nloc;
;         if (old + 1u == (gen + 1u) * nloc) {
;             __builtin_amdgcn_fence(__ATOMIC_RELEASE, "agent");
;             asm volatile("s_waitcnt vmcnt(0)" ::: "memory");
;             const unsigned og = xb_add(&bar[XB_TOP], 1u);
;             const unsigned tg = og / nx;
;             if (og + 1u == (tg + 1u) * nx) xb_add(&bar[XB_TOPGEN], 1u);
;             else XB_SPIN(xb_ld(&bar[XB_TOPGEN]) == tg, bar);
.LBB0_626:
	s_or_b64 exec, exec, s[10:11]
	v_readlane_b32 s84, v255, 2
	v_readlane_b32 s80, v255, 8
	s_mov_b64 s[6:7], 0
	s_and_b64 vcc, exec, s[8:9]
	v_readlane_b32 s85, v255, 3
	v_readlane_b32 s81, v255, 9
	s_cbranch_vccz .LBB0_680
	s_waitcnt vmcnt(0)
	s_barrier
	s_and_saveexec_b64 s[6:7], s[84:85]
	s_cbranch_execz .LBB0_679
	s_and_b32 s12, s91, 7
	s_lshl_b32 s12, s12, 7
	s_add_u32 s10, s96, 0x6000
	s_addc_u32 s11, s97, 0
	s_add_u32 s8, s10, s12
	s_addc_u32 s9, s11, 0
	v_mov_b32_e32 v1, 0
	v_mov_b32_e32 v34, 1
	s_mov_b32 s13, 0
	s_waitcnt vmcnt(0) lgkmcnt(0)
	global_atomic_add v35, v1, v34, s[8:9] sc0
	s_waitcnt vmcnt(0)
	v_cmp_eq_u32_e32 vcc, 31, v35
	s_cbranch_vccz .Lgb4_poll
	buffer_wbl2 sc1
	s_waitcnt vmcnt(0)
	global_atomic_add v1, v34, s[10:11] offset:1024
	global_atomic_add v1, v34, s[10:11] offset:1152
	global_atomic_add v1, v34, s[10:11] offset:1280
	global_atomic_add v1, v34, s[10:11] offset:1408
	global_atomic_add v1, v34, s[10:11] offset:1536
	global_atomic_add v1, v34, s[10:11] offset:1664
	global_atomic_add v1, v34, s[10:11] offset:1792
	global_atomic_add v1, v34, s[10:11] offset:1920
.Lgb4_poll:
	global_load_dword v36, v1, s[8:9] offset:1024 sc1
	s_waitcnt vmcnt(0)
	v_cmp_eq_u32_e32 vcc, 8, v36
	s_cbranch_vccnz .Lgb4_done
	s_sleep 1
	s_add_i32 s13, s13, 1
	s_cmp_lt_u32 s13, 0x10000
	s_cbranch_scc1 .Lgb4_poll

; __device__ __forceinline__ unsigned xb_ld(unsigned* p)              { return __hip_atomic_load(p, __ATOMIC_RELAXED, __HIP_MEMORY_SCOPE_AGENT); }
; __device__ __forceinline__ unsigned xb_add(unsigned* p, unsigned v) { return __hip_atomic_fetch_add(p, v, __ATOMIC_RELAXED, __HIP_MEMORY_SCOPE_AGENT); }
; #define XB_SPIN(cond, bar) do { unsigned _sp = 0; while (cond) { __builtin_amdgcn_s_sleep(1); \
;     if ((++_sp & 255u) == 0u) { if (xb_ld(&(bar)[XB_TMO])) break; if (_sp > XB_SPIN_CAP) { atomicAdd(&(bar)[XB_TMO], 1u); break; } } } } while (0)
; __device__ __forceinline__ void xcd_barrier(const XcdBarrier& b) {
;     asm volatile("s_waitcnt vmcnt(0)" ::: "memory");
;     __syncthreads();
;     if (threadIdx.x == 0) {
;         unsigned* bar = b.bar;
;         __builtin_amdgcn_s_waitcnt(0);
;         unsigned nloc = b.st[0], nx = b.st[1];
;         if (nloc == 0u) { xcd_barrier_complete(bar, b.x, nloc, nx); b.st[0] = nloc; b.st[1] = nx; }
;         const unsigned old = xb_add(&bar[XB_XSUB(b.x)], 1u);
;         const unsigned gen = old / nloc;
;         if (old + 1u == (gen + 1u) * nloc) {
;             __builtin_amdgcn_fence(__ATOMIC_RELEASE, "agent");
;             asm volatile("s_waitcnt vmcnt(0)" ::: "memory");
;             const unsigned og = xb_add(&bar[XB_TOP], 1u);
;             const unsigned tg = og / nx;
;             if (og + 1u == (tg + 1u) * nx) xb_add(&bar[XB_TOPGEN], 1u);
;             else XB_SPIN(xb_ld(&bar[XB_TOPGEN]) == tg, bar);
.LBB0_696:
.LBB0_697:
	s_cmp_gt_i32 s95, 6
	s_cbranch_scc0 .LBB0_751
	s_waitcnt vmcnt(0)
	s_barrier
	s_and_saveexec_b64 s[4:5], s[84:85]
	s_cbranch_execz .LBB0_750
	s_and_b32 s12, s91, 7
	s_lshl_b32 s12, s12, 7
	s_add_u32 s10, s96, 0x6800
	s_addc_u32 s11, s97, 0
	s_add_u32 s6, s10, s12
	s_addc_u32 s7, s11, 0
	v_mov_b32_e32 v1, 0
	v_mov_b32_e32 v2, 1
	s_mov_b32 s13, 0
	s_waitcnt vmcnt(0) lgkmcnt(0)
	global_atomic_add v3, v1, v2, s[6:7] sc0
	s_waitcnt vmcnt(0)
	v_cmp_eq_u32_e32 vcc, 31, v3
	s_cbranch_vccz .Lgb5_poll
	buffer_wbl2 sc1
	s_waitcnt vmcnt(0)
	global_atomic_add v1, v2, s[10:11] offset:1024
	global_atomic_add v1, v2, s[10:11] offset:1152
	global_atomic_add v1, v2, s[10:11] offset:1280
	global_atomic_add v1, v2, s[10:11] offset:1408
	global_atomic_add v1, v2, s[10:11] offset:1536
	global_atomic_add v1, v2, s[10:11] offset:1664
	global_atomic_add v1, v2, s[10:11] offset:1792
	global_atomic_add v1, v2, s[10:11] offset:1920
.Lgb5_poll:
	global_load_dword v4, v1, s[6:7] offset:1024 sc1
	s_waitcnt vmcnt(0)
	v_cmp_eq_u32_e32 vcc, 8, v4
	s_cbranch_vccnz .Lgb5_done
	s_sleep 1
	s_add_i32 s13, s13, 1
	s_cmp_lt_u32 s13, 0x10000
	s_cbranch_scc1 .Lgb5_poll

; __device__ __forceinline__ unsigned xb_ld(unsigned* p)              { return __hip_atomic_load(p, __ATOMIC_RELAXED, __HIP_MEMORY_SCOPE_AGENT); }
; __device__ __forceinline__ unsigned xb_add(unsigned* p, unsigned v) { return __hip_atomic_fetch_add(p, v, __ATOMIC_RELAXED, __HIP_MEMORY_SCOPE_AGENT); }
; #define XB_SPIN(cond, bar) do { unsigned _sp = 0; while (cond) { __builtin_amdgcn_s_sleep(1); \
;     if ((++_sp & 255u) == 0u) { if (xb_ld(&(bar)[XB_TMO])) break; if (_sp > XB_SPIN_CAP) { atomicAdd(&(bar)[XB_TMO], 1u); break; } } } } while (0)
; __device__ __forceinline__ void xcd_barrier(const XcdBarrier& b) {
;     asm volatile("s_waitcnt vmcnt(0)" ::: "memory");
;     __syncthreads();
;     if (threadIdx.x == 0) {
;         unsigned* bar = b.bar;
;         __builtin_amdgcn_s_waitcnt(0);
;         unsigned nloc = b.st[0], nx = b.st[1];
;         if (nloc == 0u) { xcd_barrier_complete(bar, b.x, nloc, nx); b.st[0] = nloc; b.st[1] = nx; }
;         const unsigned old = xb_add(&bar[XB_XSUB(b.x)], 1u);
;         const unsigned gen = old / nloc;
;         if (old + 1u == (gen + 1u) * nloc) {
;             __builtin_amdgcn_fence(__ATOMIC_RELEASE, "agent");
;             asm volatile("s_waitcnt vmcnt(0)" ::: "memory");
;             const unsigned og = xb_add(&bar[XB_TOP], 1u);
;             const unsigned tg = og / nx;
;             if (og + 1u == (tg + 1u) * nx) xb_add(&bar[XB_TOPGEN], 1u);
;             else XB_SPIN(xb_ld(&bar[XB_TOPGEN]) == tg, bar);
.LBB0_795:
	s_waitcnt vmcnt(0)
	s_waitcnt lgkmcnt(0)
	s_barrier
	s_and_saveexec_b64 s[4:5], s[84:85]
	s_cbranch_execz .LBB0_847
	s_and_b32 s12, s91, 7
	s_lshl_b32 s12, s12, 7
	s_add_u32 s8, s96, 0x7000
	s_addc_u32 s9, s97, 0
	s_add_u32 s6, s8, s12
	s_addc_u32 s7, s9, 0
	v_mov_b32_e32 v1, 0
	v_mov_b32_e32 v2, 1
	s_mov_b32 s13, 0
	s_waitcnt vmcnt(0) lgkmcnt(0)
	global_atomic_add v3, v1, v2, s[6:7] sc0
	s_waitcnt vmcnt(0)
	v_cmp_eq_u32_e32 vcc, 31, v3
	s_cbranch_vccz .Lgb6_poll
	buffer_wbl2 sc1
	s_waitcnt vmcnt(0)
	global_atomic_add v1, v2, s[8:9] offset:1024
	global_atomic_add v1, v2, s[8:9] offset:1152
	global_atomic_add v1, v2, s[8:9] offset:1280
	global_atomic_add v1, v2, s[8:9] offset:1408
	global_atomic_add v1, v2, s[8:9] offset:1536
	global_atomic_add v1, v2, s[8:9] offset:1664
	global_atomic_add v1, v2, s[8:9] offset:1792
	global_atomic_add v1, v2, s[8:9] offset:1920

; __device__ __forceinline__ unsigned xb_ld(unsigned* p)              { return __hip_atomic_load(p, __ATOMIC_RELAXED, __HIP_MEMORY_SCOPE_AGENT); }
; __device__ __forceinline__ unsigned xb_add(unsigned* p, unsigned v) { return __hip_atomic_fetch_add(p, v, __ATOMIC_RELAXED, __HIP_MEMORY_SCOPE_AGENT); }
; #define XB_SPIN(cond, bar) do { unsigned _sp = 0; while (cond) { __builtin_amdgcn_s_sleep(1); \
;     if ((++_sp & 255u) == 0u) { if (xb_ld(&(bar)[XB_TMO])) break; if (_sp > XB_SPIN_CAP) { atomicAdd(&(bar)[XB_TMO], 1u); break; } } } } while (0)
; __device__ __forceinline__ void xcd_barrier(const XcdBarrier& b) {
;     asm volatile("s_waitcnt vmcnt(0)" ::: "memory");
;     __syncthreads();
;     if (threadIdx.x == 0) {
;         unsigned* bar = b.bar;
;         __builtin_amdgcn_s_waitcnt(0);
;         unsigned nloc = b.st[0], nx = b.st[1];
;         if (nloc == 0u) { xcd_barrier_complete(bar, b.x, nloc, nx); b.st[0] = nloc; b.st[1] = nx; }
;         const unsigned old = xb_add(&bar[XB_XSUB(b.x)], 1u);
;         const unsigned gen = old / nloc;
;         if (old + 1u == (gen + 1u) * nloc) {
;             __builtin_amdgcn_fence(__ATOMIC_RELEASE, "agent");
;             asm volatile("s_waitcnt vmcnt(0)" ::: "memory");
;             const unsigned og = xb_add(&bar[XB_TOP], 1u);
;             const unsigned tg = og / nx;
;             if (og + 1u == (tg + 1u) * nx) xb_add(&bar[XB_TOPGEN], 1u);
;             else XB_SPIN(xb_ld(&bar[XB_TOPGEN]) == tg, bar);
.LBB0_924:
	s_cmp_gt_i32 s95, 9
	s_cbranch_scc0 .LBB0_978
	s_waitcnt vmcnt(0)
	s_barrier
	s_and_saveexec_b64 s[4:5], s[84:85]
	s_cbranch_execz .LBB0_977
	s_and_b32 s3, s91, 7
	s_lshl_b32 s3, s3, 7
	s_add_u32 s8, s96, 0x7800
	s_addc_u32 s9, s97, 0
	s_add_u32 s6, s8, s3
	s_addc_u32 s7, s9, 0
	v_mov_b32_e32 v1, 0
	v_mov_b32_e32 v2, 1
	s_mov_b32 s10, 0
	s_waitcnt vmcnt(0) lgkmcnt(0)
	global_atomic_add v3, v1, v2, s[6:7] sc0
	s_waitcnt vmcnt(0)
	v_cmp_eq_u32_e32 vcc, 31, v3
	s_cbranch_vccz .Lgb7_poll
	buffer_wbl2 sc1
	s_waitcnt vmcnt(0)
	global_atomic_add v1, v2, s[8:9] offset:1024
	global_atomic_add v1, v2, s[8:9] offset:1152
	global_atomic_add v1, v2, s[8:9] offset:1280
	global_atomic_add v1, v2, s[8:9] offset:1408
	global_atomic_add v1, v2, s[8:9] offset:1536
	global_atomic_add v1, v2, s[8:9] offset:1664
	global_atomic_add v1, v2, s[8:9] offset:1792
	global_atomic_add v1, v2, s[8:9] offset:1920

; __device__ __forceinline__ unsigned xb_ld(unsigned* p)              { return __hip_atomic_load(p, __ATOMIC_RELAXED, __HIP_MEMORY_SCOPE_AGENT); }
; __device__ __forceinline__ unsigned xb_add(unsigned* p, unsigned v) { return __hip_atomic_fetch_add(p, v, __ATOMIC_RELAXED, __HIP_MEMORY_SCOPE_AGENT); }
; #define XB_SPIN(cond, bar) do { unsigned _sp = 0; while (cond) { __builtin_amdgcn_s_sleep(1); \
;     if ((++_sp & 255u) == 0u) { if (xb_ld(&(bar)[XB_TMO])) break; if (_sp > XB_SPIN_CAP) { atomicAdd(&(bar)[XB_TMO], 1u); break; } } } } while (0)
; __device__ __forceinline__ void xcd_barrier(const XcdBarrier& b) {
;     asm volatile("s_waitcnt vmcnt(0)" ::: "memory");
;     __syncthreads();
;     if (threadIdx.x == 0) {
;         unsigned* bar = b.bar;
;         __builtin_amdgcn_s_waitcnt(0);
;         unsigned nloc = b.st[0], nx = b.st[1];
;         if (nloc == 0u) { xcd_barrier_complete(bar, b.x, nloc, nx); b.st[0] = nloc; b.st[1] = nx; }
;         const unsigned old = xb_add(&bar[XB_XSUB(b.x)], 1u);
;         const unsigned gen = old / nloc;
;         if (old + 1u == (gen + 1u) * nloc) {
;             __builtin_amdgcn_fence(__ATOMIC_RELEASE, "agent");
;             asm volatile("s_waitcnt vmcnt(0)" ::: "memory");
;             const unsigned og = xb_add(&bar[XB_TOP], 1u);
;             const unsigned tg = og / nx;
;             if (og + 1u == (tg + 1u) * nx) xb_add(&bar[XB_TOPGEN], 1u);
;             else XB_SPIN(xb_ld(&bar[XB_TOPGEN]) == tg, bar);
;             __builtin_amdgcn_fence(__ATOMIC_ACQUIRE, "agent");
;             xb_add(&bar[XB_XGEN(b.x)], 1u);
;             asm volatile("s_waitcnt vmcnt(0)" ::: "memory");
;         } else {
;             XB_SPIN(xb_ld(&bar[XB_XGEN(b.x)]) == gen, bar);
;             __builtin_amdgcn_fence(__ATOMIC_ACQUIRE, "agent");
;             asm volatile("s_waitcnt vmcnt(0)" ::: "memory");
;         }
;     }
;     __syncthreads();
; }
.LBB0_1007:
	s_cmp_lt_i32 s95, 12
	s_cbranch_scc1 .LBB0_1061
	s_waitcnt vmcnt(0)
	s_barrier
	s_and_saveexec_b64 s[2:3], s[84:85]
	s_cbranch_execz .LBB0_1060
	s_and_b32 s8, s91, 7
	s_lshl_b32 s8, s8, 7
	s_add_u32 s6, s96, 0x8000
	s_addc_u32 s7, s97, 0
	s_add_u32 s4, s6, s8
	s_addc_u32 s5, s7, 0
	v_mov_b32_e32 v0, 0
	v_mov_b32_e32 v1, 1
	s_mov_b32 s9, 0
	s_waitcnt vmcnt(0) lgkmcnt(0)
	global_atomic_add v2, v0, v1, s[4:5] sc0
	s_waitcnt vmcnt(0)
	v_cmp_eq_u32_e32 vcc, 31, v2
	s_cbranch_vccz .Lgb8_poll
	buffer_wbl2 sc1
	s_waitcnt vmcnt(0)
	global_atomic_add v0, v1, s[6:7] offset:1024
	global_atomic_add v0, v1, s[6:7] offset:1152
	global_atomic_add v0, v1, s[6:7] offset:1280
	global_atomic_add v0, v1, s[6:7] offset:1408
	global_atomic_add v0, v1, s[6:7] offset:1536
	global_atomic_add v0, v1, s[6:7] offset:1664
	global_atomic_add v0, v1, s[6:7] offset:1792
	global_atomic_add v0, v1, s[6:7] offset:1920
.Lgb8_poll:
	global_load_dword v3, v0, s[4:5] offset:1024 sc1
	s_waitcnt vmcnt(0)
	v_cmp_eq_u32_e32 vcc, 8, v3
	s_cbranch_vccnz .Lgb8_done
	s_sleep 1
	s_add_i32 s9, s9, 1
	s_cmp_lt_u32 s9, 0x10000
	s_cbranch_scc1 .Lgb8_poll
